# stack + redundant lgkmcnt waits in front of the attention QK^T MFMAs deleted + permlane swaps for the out-projection row-stat sums
# speedup vs baseline: 1.0065x; 1.0006x over previous
.LBB0_485:
	v_add_u32_e32 v192, s30, v229
	ds_read_b64_tr_b16 v[224:225], v192 offset:24576
	ds_read_b64_tr_b16 v[226:227], v192 offset:25088
	v_add_f32_e32 v102, v82, v83
	v_add_f32_e32 v102, v84, v102
	v_add_f32_e32 v102, v85, v102
	v_add_f32_e32 v102, v86, v102
	v_add_f32_e32 v102, v87, v102
	v_cvt_pk_bf16_f32 v166, v82, v83
	v_cvt_pk_bf16_f32 v167, v84, v85
	v_mfma_f32_32x32x16_bf16 v[114:129], v[98:101], v[174:177], v[18:33]
	ds_read_b64_tr_b16 v[82:83], v192 offset:28672
	ds_read_b64_tr_b16 v[84:85], v192 offset:29184
	v_add_f32_e32 v98, v88, v102
	v_add_f32_e32 v98, v89, v98
	v_add_f32_e32 v98, v90, v98
	v_add_f32_e32 v146, v91, v98
	v_mfma_f32_32x32x16_bf16 v[98:113], v[186:189], v[174:177], v[18:33]
	v_cvt_pk_bf16_f32 v168, v86, v87
	v_cvt_pk_bf16_f32 v169, v88, v89
	ds_read_b64_tr_b16 v[86:87], v192 offset:25600
	ds_read_b64_tr_b16 v[88:89], v192 offset:26112
	v_add_f32_e32 v146, v92, v146
	v_add_f32_e32 v146, v93, v146
	v_add_f32_e32 v146, v94, v146
	v_add_f32_e32 v146, v95, v146
	v_cvt_pk_bf16_f32 v158, v90, v91
	v_cvt_pk_bf16_f32 v159, v92, v93
	v_mfma_f32_32x32x16_bf16 v[114:129], v[182:185], v[170:173], v[114:129]
	ds_read_b64_tr_b16 v[90:91], v192 offset:29696
	ds_read_b64_tr_b16 v[92:93], v192 offset:30208
	v_mfma_f32_32x32x16_bf16 v[98:113], v[178:181], v[170:173], v[98:113]
	v_add_f32_e32 v146, v96, v146
	v_add_f32_e32 v146, v97, v146
	v_add_f32_e32 v146, v66, v146
	v_add_f32_e32 v146, v67, v146
	v_cvt_pk_bf16_f32 v160, v94, v95
	v_cvt_pk_bf16_f32 v161, v96, v97
	ds_read_b64_tr_b16 v[94:95], v192 offset:26624
	ds_read_b64_tr_b16 v[96:97], v192 offset:27136
	v_add_f32_e32 v146, v68, v146
	v_add_f32_e32 v146, v69, v146
	v_add_f32_e32 v146, v70, v146
	v_add_f32_e32 v146, v71, v146
	v_cvt_pk_bf16_f32 v150, v66, v67
	v_cvt_pk_bf16_f32 v151, v68, v69
	v_mfma_f32_32x32x16_bf16 v[114:129], v[142:145], v[162:165], v[114:129]
	ds_read_b64_tr_b16 v[66:67], v192 offset:30720
	ds_read_b64_tr_b16 v[68:69], v192 offset:31232
	v_mfma_f32_32x32x16_bf16 v[98:113], v[138:141], v[162:165], v[98:113]
	v_add_f32_e32 v142, v72, v146
	v_add_f32_e32 v142, v73, v142
	v_add_f32_e32 v142, v74, v142
	v_add_f32_e32 v142, v75, v142
	v_cvt_pk_bf16_f32 v152, v70, v71
	v_cvt_pk_bf16_f32 v153, v72, v73
	ds_read_b64_tr_b16 v[70:71], v192 offset:27648
	ds_read_b64_tr_b16 v[72:73], v192 offset:28160
	v_add_f32_e32 v138, v76, v142
	v_add_f32_e32 v138, v77, v138
	v_add_f32_e32 v138, v78, v138
	v_add_f32_e32 v138, v79, v138
	v_cvt_pk_bf16_f32 v146, v74, v75
	v_cvt_pk_bf16_f32 v147, v76, v77
	v_mfma_f32_32x32x16_bf16 v[114:129], v[134:137], v[154:157], v[114:129]
	ds_read_b64_tr_b16 v[74:75], v192 offset:31744
	ds_read_b64_tr_b16 v[76:77], v192 offset:32256
	v_mfma_f32_32x32x16_bf16 v[98:113], v[130:133], v[154:157], v[98:113]
	v_add_f32_e32 v134, v80, v138
	v_add_f32_e32 v134, v81, v134
	v_add_f32_e32 v134, 0, v134
	v_cvt_pk_bf16_f32 v148, v78, v79
	v_cvt_pk_bf16_f32 v149, v80, v81
	v_lshl_add_u64 v[78:79], v[220:221], 0, s[12:13]
	s_add_i32 s6, s29, s59
	s_mov_b32 s30, m0
	s_mov_b32 m0, s6
	s_nop 0
	global_load_lds_dwordx4 v[78:79], off
	s_mov_b32 m0, s30
	v_lshl_add_u64 v[78:79], v[222:223], 0, s[8:9]
	s_add_i32 s6, s28, s58
	s_mov_b32 s30, m0
	s_mov_b32 m0, s6
	s_nop 0
	global_load_lds_dwordx4 v[78:79], off
	s_mov_b32 m0, s30
	v_add_f32_e32 v192, v201, v134
	s_waitcnt lgkmcnt(14)
	v_mfma_f32_32x32x16_bf16 v[34:49], v[166:169], v[224:227], v[34:49]
	v_exp_f32_e32 v114, v114
	v_exp_f32_e32 v115, v115
	v_exp_f32_e32 v116, v116
	v_exp_f32_e32 v117, v117
	s_waitcnt lgkmcnt(12)
	v_mfma_f32_32x32x16_bf16 v[50:65], v[166:169], v[82:85], v[50:65]
	v_exp_f32_e32 v118, v118
	v_exp_f32_e32 v119, v119
	v_exp_f32_e32 v120, v120
	v_exp_f32_e32 v121, v121
	v_add_u32_e32 v82, s28, v228
	ds_read_b128 v[78:81], v82
	ds_read_b128 v[130:133], v82 offset:512
	s_waitcnt lgkmcnt(12)
	v_mfma_f32_32x32x16_bf16 v[34:49], v[158:161], v[86:89], v[34:49]
	v_exp_f32_e32 v122, v122
	v_exp_f32_e32 v123, v123
	v_exp_f32_e32 v124, v124
	v_exp_f32_e32 v125, v125
	ds_read_b128 v[134:137], v82 offset:2048
	ds_read_b128 v[138:141], v82 offset:2560
	s_waitcnt lgkmcnt(12)
	v_mfma_f32_32x32x16_bf16 v[50:65], v[158:161], v[90:93], v[50:65]
	v_exp_f32_e32 v126, v126
	v_exp_f32_e32 v127, v127
	v_exp_f32_e32 v128, v128
	v_exp_f32_e32 v129, v129
	ds_read_b128 v[142:145], v82 offset:4096
	ds_read_b128 v[178:181], v82 offset:4608
	s_waitcnt lgkmcnt(12)
	v_mfma_f32_32x32x16_bf16 v[34:49], v[150:153], v[94:97], v[34:49]
	v_exp_f32_e32 v98, v98
	v_exp_f32_e32 v99, v99
	v_exp_f32_e32 v100, v100
	v_exp_f32_e32 v101, v101
	ds_read_b128 v[182:185], v82 offset:6144
	ds_read_b128 v[186:189], v82 offset:6656
	s_waitcnt lgkmcnt(12)
	v_mfma_f32_32x32x16_bf16 v[50:65], v[150:153], v[66:69], v[50:65]
	v_exp_f32_e32 v102, v102
	v_exp_f32_e32 v103, v103
	v_exp_f32_e32 v104, v104
	v_exp_f32_e32 v105, v105
	s_waitcnt lgkmcnt(10)
	v_mfma_f32_32x32x16_bf16 v[34:49], v[146:149], v[70:73], v[34:49]
	v_exp_f32_e32 v106, v106
	v_exp_f32_e32 v107, v107
	v_exp_f32_e32 v108, v108
	v_exp_f32_e32 v109, v109
	s_waitcnt lgkmcnt(8)
	v_mfma_f32_32x32x16_bf16 v[50:65], v[146:149], v[74:77], v[50:65]
	v_exp_f32_e32 v110, v110
	v_exp_f32_e32 v111, v111
	v_exp_f32_e32 v112, v112
	v_exp_f32_e32 v113, v113
	s_waitcnt vmcnt(2) lgkmcnt(0)
	s_barrier
	s_add_i32 s6, s28, 0x2000
	s_cmpk_lg_i32 s28, 0x4000
	s_cselect_b32 s6, s6, 0
	v_add_u32_e32 v201, s29, v229
	ds_read_b64_tr_b16 v[224:225], v201 offset:24576
	ds_read_b64_tr_b16 v[226:227], v201 offset:25088
	v_mfma_f32_32x32x16_bf16 v[82:97], v[78:81], v[174:177], v[18:33]
	v_add_f32_e32 v66, v114, v115
	v_add_f32_e32 v66, v116, v66
	v_add_f32_e32 v66, v117, v66
	v_add_f32_e32 v66, v118, v66
	v_add_f32_e32 v66, v119, v66
	v_cvt_pk_bf16_f32 v166, v114, v115
	v_cvt_pk_bf16_f32 v167, v116, v117
	ds_read_b64_tr_b16 v[114:115], v201 offset:28672
	ds_read_b64_tr_b16 v[116:117], v201 offset:29184
	v_add_f32_e32 v66, v120, v66
	v_add_f32_e32 v66, v121, v66
	v_add_f32_e32 v66, v122, v66
	v_add_f32_e32 v146, v123, v66
	v_mfma_f32_32x32x16_bf16 v[66:81], v[130:133], v[174:177], v[18:33]
	v_cvt_pk_bf16_f32 v168, v118, v119
	v_cvt_pk_bf16_f32 v169, v120, v121
	ds_read_b64_tr_b16 v[118:119], v201 offset:25600
	ds_read_b64_tr_b16 v[120:121], v201 offset:26112
	v_mfma_f32_32x32x16_bf16 v[82:97], v[134:137], v[170:173], v[82:97]
	v_add_f32_e32 v130, v124, v146
	v_add_f32_e32 v130, v125, v130
	v_add_f32_e32 v130, v126, v130
	v_add_f32_e32 v130, v127, v130
	v_cvt_pk_bf16_f32 v158, v122, v123
	v_cvt_pk_bf16_f32 v159, v124, v125
	ds_read_b64_tr_b16 v[122:123], v201 offset:29696
	ds_read_b64_tr_b16 v[124:125], v201 offset:30208
	v_mfma_f32_32x32x16_bf16 v[66:81], v[138:141], v[170:173], v[66:81]
	v_add_f32_e32 v130, v128, v130
	v_add_f32_e32 v130, v129, v130
	v_add_f32_e32 v130, v98, v130
	v_add_f32_e32 v130, v99, v130
	v_cvt_pk_bf16_f32 v160, v126, v127
	v_cvt_pk_bf16_f32 v161, v128, v129
	ds_read_b64_tr_b16 v[126:127], v201 offset:26624
	ds_read_b64_tr_b16 v[128:129], v201 offset:27136
	v_mfma_f32_32x32x16_bf16 v[82:97], v[142:145], v[162:165], v[82:97]
	v_add_f32_e32 v130, v100, v130
	v_add_f32_e32 v130, v101, v130
	v_add_f32_e32 v130, v102, v130
	v_add_f32_e32 v130, v103, v130
	v_cvt_pk_bf16_f32 v150, v98, v99
	v_cvt_pk_bf16_f32 v151, v100, v101
	ds_read_b64_tr_b16 v[240:241], v201 offset:30720
	ds_read_b64_tr_b16 v[242:243], v201 offset:31232
	v_mfma_f32_32x32x16_bf16 v[66:81], v[178:181], v[162:165], v[66:81]
	v_add_f32_e32 v98, v104, v130
	v_add_f32_e32 v98, v105, v98
	v_add_f32_e32 v98, v106, v98
	v_add_f32_e32 v98, v107, v98
	v_cvt_pk_bf16_f32 v152, v102, v103
	v_cvt_pk_bf16_f32 v153, v104, v105
	ds_read_b64_tr_b16 v[102:103], v201 offset:27648
	ds_read_b64_tr_b16 v[104:105], v201 offset:28160
	v_mfma_f32_32x32x16_bf16 v[82:97], v[182:185], v[154:157], v[82:97]
	v_add_f32_e32 v98, v108, v98
	v_add_f32_e32 v98, v109, v98
	v_add_f32_e32 v98, v110, v98
	v_add_f32_e32 v98, v111, v98
	v_cvt_pk_bf16_f32 v146, v106, v107
	v_cvt_pk_bf16_f32 v147, v108, v109
	ds_read_b64_tr_b16 v[106:107], v201 offset:31744
	ds_read_b64_tr_b16 v[108:109], v201 offset:32256
	v_mfma_f32_32x32x16_bf16 v[66:81], v[186:189], v[154:157], v[66:81]
	v_add_f32_e32 v98, v112, v98
	v_add_f32_e32 v98, v113, v98
	v_add_f32_e32 v98, 0, v98
	v_cvt_pk_bf16_f32 v148, v110, v111
	v_cvt_pk_bf16_f32 v149, v112, v113
	s_nop 0
	v_add_f32_e32 v201, v192, v98
	v_lshl_add_u64 v[98:99], v[220:221], 0, s[14:15]
	s_add_i32 s29, s28, s59
	s_mov_b32 s30, m0
	s_mov_b32 m0, s29
	s_nop 0
	global_load_lds_dwordx4 v[98:99], off
	s_mov_b32 m0, s30
	v_lshl_add_u64 v[222:223], v[222:223], 0, s[10:11]
	s_add_i32 s29, s6, s58
	s_mov_b32 s30, m0
	s_mov_b32 m0, s29
	s_nop 0
	global_load_lds_dwordx4 v[222:223], off
	s_mov_b32 m0, s30
	s_waitcnt lgkmcnt(14)
	v_mfma_f32_32x32x16_bf16 v[34:49], v[166:169], v[224:227], v[34:49]
	v_exp_f32_e32 v82, v82
	v_exp_f32_e32 v83, v83
	v_exp_f32_e32 v84, v84
	v_exp_f32_e32 v85, v85
	s_waitcnt lgkmcnt(12)
	v_mfma_f32_32x32x16_bf16 v[50:65], v[166:169], v[114:117], v[50:65]
	v_exp_f32_e32 v86, v86
	v_exp_f32_e32 v87, v87
	v_exp_f32_e32 v88, v88
	v_exp_f32_e32 v89, v89
	v_add_u32_e32 v110, s6, v228
	ds_read_b128 v[98:101], v110
	ds_read_b128 v[186:189], v110 offset:512
	s_waitcnt lgkmcnt(12)
	v_mfma_f32_32x32x16_bf16 v[34:49], v[158:161], v[118:121], v[34:49]
	v_exp_f32_e32 v90, v90
	v_exp_f32_e32 v91, v91
	v_exp_f32_e32 v92, v92
	v_exp_f32_e32 v93, v93
	ds_read_b128 v[182:185], v110 offset:2048
	ds_read_b128 v[178:181], v110 offset:2560
	s_waitcnt lgkmcnt(12)
	v_mfma_f32_32x32x16_bf16 v[50:65], v[158:161], v[122:125], v[50:65]
	v_exp_f32_e32 v94, v94
	v_exp_f32_e32 v95, v95
	v_exp_f32_e32 v96, v96
	v_exp_f32_e32 v97, v97
	ds_read_b128 v[142:145], v110 offset:4096
	ds_read_b128 v[138:141], v110 offset:4608
	s_waitcnt lgkmcnt(12)
	v_mfma_f32_32x32x16_bf16 v[34:49], v[150:153], v[126:129], v[34:49]
	v_exp_f32_e32 v66, v66
	v_exp_f32_e32 v67, v67
	v_exp_f32_e32 v68, v68
	v_exp_f32_e32 v69, v69
	ds_read_b128 v[134:137], v110 offset:6144
	ds_read_b128 v[130:133], v110 offset:6656
	s_waitcnt lgkmcnt(12)
	v_mfma_f32_32x32x16_bf16 v[50:65], v[150:153], v[240:243], v[50:65]
	v_exp_f32_e32 v70, v70
	v_exp_f32_e32 v71, v71
	v_exp_f32_e32 v72, v72
	v_exp_f32_e32 v73, v73
	s_waitcnt lgkmcnt(10)
	v_mfma_f32_32x32x16_bf16 v[34:49], v[146:149], v[102:105], v[34:49]
	v_exp_f32_e32 v74, v74
	v_exp_f32_e32 v75, v75
	v_exp_f32_e32 v76, v76
	v_exp_f32_e32 v77, v77
	s_waitcnt lgkmcnt(8)
	v_mfma_f32_32x32x16_bf16 v[50:65], v[146:149], v[106:109], v[50:65]
	v_exp_f32_e32 v78, v78
	v_exp_f32_e32 v79, v79
	v_exp_f32_e32 v80, v80
	v_exp_f32_e32 v81, v81
	s_add_i32 s31, s6, 0x2000
	s_waitcnt vmcnt(2) lgkmcnt(0)
	s_barrier
	s_cmpk_lg_i32 s6, 0x4000
	s_mov_b32 s30, s28
	s_cselect_b32 s28, s31, 0
	s_add_i32 s2, s2, 2
	v_lshl_add_u64 v[220:221], v[220:221], 0, s[10:11]
	s_mov_b32 s29, s6
	s_cmp_gt_u32 s2, 24
	s_cbranch_scc0 .LBB0_485
	ds_read_b64_tr_b16 v[220:221], v229 offset:40960
	ds_read_b64_tr_b16 v[222:223], v229 offset:41472
	v_add_f32_e32 v102, v82, v83
	v_add_f32_e32 v102, v84, v102
	v_add_f32_e32 v102, v85, v102
	v_add_f32_e32 v102, v86, v102
	v_add_f32_e32 v102, v87, v102
	v_cvt_pk_bf16_f32 v166, v82, v83
	v_cvt_pk_bf16_f32 v167, v84, v85
	v_mfma_f32_32x32x16_bf16 v[114:129], v[98:101], v[174:177], v[18:33]
	ds_read_b64_tr_b16 v[82:83], v229 offset:45056
	ds_read_b64_tr_b16 v[84:85], v229 offset:45568
	v_add_f32_e32 v98, v88, v102
	v_add_f32_e32 v98, v89, v98
	v_add_f32_e32 v98, v90, v98
	v_add_f32_e32 v146, v91, v98
	v_mfma_f32_32x32x16_bf16 v[98:113], v[186:189], v[174:177], v[18:33]
	v_cvt_pk_bf16_f32 v168, v86, v87
	v_cvt_pk_bf16_f32 v169, v88, v89
	ds_read_b64_tr_b16 v[86:87], v229 offset:41984
	ds_read_b64_tr_b16 v[88:89], v229 offset:42496
	v_add_f32_e32 v146, v92, v146
	v_add_f32_e32 v146, v93, v146
	v_add_f32_e32 v146, v94, v146
	v_add_f32_e32 v146, v95, v146
	v_cvt_pk_bf16_f32 v158, v90, v91
	v_cvt_pk_bf16_f32 v159, v92, v93
	v_mfma_f32_32x32x16_bf16 v[114:129], v[182:185], v[170:173], v[114:129]
	ds_read_b64_tr_b16 v[90:91], v229 offset:46080
	ds_read_b64_tr_b16 v[92:93], v229 offset:46592
	v_mfma_f32_32x32x16_bf16 v[98:113], v[178:181], v[170:173], v[98:113]
	v_add_f32_e32 v146, v96, v146
	v_add_f32_e32 v146, v97, v146
	v_add_f32_e32 v146, v66, v146
	v_add_f32_e32 v146, v67, v146
	v_cvt_pk_bf16_f32 v160, v94, v95
	v_cvt_pk_bf16_f32 v161, v96, v97
	ds_read_b64_tr_b16 v[94:95], v229 offset:43008
	ds_read_b64_tr_b16 v[96:97], v229 offset:43520
	v_add_f32_e32 v146, v68, v146
	v_add_f32_e32 v146, v69, v146
	v_add_f32_e32 v146, v70, v146
	v_add_f32_e32 v146, v71, v146
	v_cvt_pk_bf16_f32 v150, v66, v67
	v_cvt_pk_bf16_f32 v151, v68, v69
	v_mfma_f32_32x32x16_bf16 v[114:129], v[142:145], v[162:165], v[114:129]
	ds_read_b64_tr_b16 v[66:67], v229 offset:47104
	ds_read_b64_tr_b16 v[68:69], v229 offset:47616
	v_mfma_f32_32x32x16_bf16 v[98:113], v[138:141], v[162:165], v[98:113]
	v_add_f32_e32 v142, v72, v146
	v_add_f32_e32 v142, v73, v142
	v_add_f32_e32 v142, v74, v142
	v_add_f32_e32 v142, v75, v142
	v_cvt_pk_bf16_f32 v152, v70, v71
	v_cvt_pk_bf16_f32 v153, v72, v73
	ds_read_b64_tr_b16 v[70:71], v229 offset:44032
	ds_read_b64_tr_b16 v[72:73], v229 offset:44544
	v_add_f32_e32 v138, v76, v142
	v_add_f32_e32 v138, v77, v138
	v_add_f32_e32 v138, v78, v138
	v_add_f32_e32 v138, v79, v138
	v_cvt_pk_bf16_f32 v146, v74, v75
	v_cvt_pk_bf16_f32 v147, v76, v77
	v_mfma_f32_32x32x16_bf16 v[114:129], v[134:137], v[154:157], v[114:129]
	ds_read_b64_tr_b16 v[74:75], v229 offset:48128
	ds_read_b64_tr_b16 v[76:77], v229 offset:48640
	v_mfma_f32_32x32x16_bf16 v[98:113], v[130:133], v[154:157], v[98:113]
	v_add_f32_e32 v134, v80, v138
	v_add_f32_e32 v134, v81, v134
	v_add_f32_e32 v178, 0, v134
	v_cvt_pk_bf16_f32 v148, v78, v79
	v_cvt_pk_bf16_f32 v149, v80, v81
	s_cmp_lg_u32 0, -1
	s_cselect_b32 s6, 0, 0
	v_lshl_add_u64 v[78:79], v[214:215], 0, s[16:17]
	s_mov_b32 s2, m0
	s_mov_b32 m0, s59
	s_nop 0
	global_load_lds_dwordx4 v[78:79], off
	s_mov_b32 m0, s2
	s_add_i32 s6, s6, s57
	v_lshl_add_u64 v[78:79], v[216:217], 0, s[18:19]
	s_add_i32 s2, s6, 0x8000
	s_mov_b32 s28, m0
	s_mov_b32 m0, s2
	s_nop 0
	global_load_lds_dwordx4 v[78:79], off
	s_mov_b32 m0, s28
	s_waitcnt lgkmcnt(14)
	v_mfma_f32_32x32x16_bf16 v[34:49], v[166:169], v[220:223], v[34:49]
	v_exp_f32_e32 v114, v114
	v_exp_f32_e32 v115, v115
	v_exp_f32_e32 v116, v116
	v_exp_f32_e32 v117, v117
	s_waitcnt lgkmcnt(12)
	v_mfma_f32_32x32x16_bf16 v[50:65], v[166:169], v[82:85], v[50:65]
	v_exp_f32_e32 v118, v118
	v_exp_f32_e32 v119, v119
	v_exp_f32_e32 v120, v120
	v_exp_f32_e32 v121, v121
	ds_read_b128 v[78:81], v228 offset:8192
	ds_read_b128 v[130:133], v228 offset:8704
	s_waitcnt lgkmcnt(12)
	v_mfma_f32_32x32x16_bf16 v[34:49], v[158:161], v[86:89], v[34:49]
	v_exp_f32_e32 v122, v122
	v_exp_f32_e32 v123, v123
	v_exp_f32_e32 v124, v124
	v_exp_f32_e32 v125, v125
	ds_read_b128 v[134:137], v228 offset:10240
	ds_read_b128 v[138:141], v228 offset:10752
	s_waitcnt lgkmcnt(12)
	v_mfma_f32_32x32x16_bf16 v[50:65], v[158:161], v[90:93], v[50:65]
	v_exp_f32_e32 v126, v126
	v_exp_f32_e32 v127, v127
	v_exp_f32_e32 v128, v128
	v_exp_f32_e32 v129, v129
	ds_read_b128 v[142:145], v228 offset:12288
	ds_read_b128 v[180:183], v228 offset:12800
	s_waitcnt lgkmcnt(12)
	v_mfma_f32_32x32x16_bf16 v[34:49], v[150:153], v[94:97], v[34:49]
	v_exp_f32_e32 v98, v98
	v_exp_f32_e32 v99, v99
	v_exp_f32_e32 v100, v100
	v_exp_f32_e32 v101, v101
	ds_read_b128 v[184:187], v228 offset:14336
	ds_read_b128 v[220:223], v228 offset:14848
	s_waitcnt lgkmcnt(12)
	v_mfma_f32_32x32x16_bf16 v[50:65], v[150:153], v[66:69], v[50:65]
	v_exp_f32_e32 v102, v102
	v_exp_f32_e32 v103, v103
	v_exp_f32_e32 v104, v104
	v_exp_f32_e32 v105, v105
	s_waitcnt lgkmcnt(10)
	v_mfma_f32_32x32x16_bf16 v[34:49], v[146:149], v[70:73], v[34:49]
	v_exp_f32_e32 v106, v106
	v_exp_f32_e32 v107, v107
	v_exp_f32_e32 v108, v108
	v_exp_f32_e32 v109, v109
	s_waitcnt lgkmcnt(8)
	v_mfma_f32_32x32x16_bf16 v[50:65], v[146:149], v[74:77], v[50:65]
	v_exp_f32_e32 v110, v110
	v_exp_f32_e32 v111, v111
	v_exp_f32_e32 v112, v112
	v_exp_f32_e32 v113, v113
	s_waitcnt vmcnt(2) lgkmcnt(0)
	s_barrier
	ds_read_b64_tr_b16 v[240:241], v229 offset:24576
	ds_read_b64_tr_b16 v[242:243], v229 offset:25088
	v_add_f32_e32 v66, v114, v115
	v_add_f32_e32 v66, v116, v66
	v_add_f32_e32 v66, v117, v66
	v_add_f32_e32 v66, v118, v66
	v_add_f32_e32 v66, v119, v66
	v_cvt_pk_bf16_f32 v166, v114, v115
	v_cvt_pk_bf16_f32 v167, v116, v117
	v_mfma_f32_32x32x16_bf16 v[82:97], v[78:81], v[174:177], v[18:33]
	ds_read_b64_tr_b16 v[114:115], v229 offset:28672
	ds_read_b64_tr_b16 v[116:117], v229 offset:29184
	v_add_f32_e32 v66, v120, v66
	v_add_f32_e32 v66, v121, v66
	v_add_f32_e32 v66, v122, v66
	v_add_f32_e32 v146, v123, v66
	v_mfma_f32_32x32x16_bf16 v[66:81], v[130:133], v[174:177], v[18:33]
	v_cvt_pk_bf16_f32 v168, v118, v119
	v_cvt_pk_bf16_f32 v169, v120, v121
	ds_read_b64_tr_b16 v[118:119], v229 offset:25600
	ds_read_b64_tr_b16 v[120:121], v229 offset:26112
	v_add_f32_e32 v130, v124, v146
	v_add_f32_e32 v130, v125, v130
	v_add_f32_e32 v130, v126, v130
	v_add_f32_e32 v130, v127, v130
	v_cvt_pk_bf16_f32 v158, v122, v123
	v_cvt_pk_bf16_f32 v159, v124, v125
	v_mfma_f32_32x32x16_bf16 v[82:97], v[134:137], v[170:173], v[82:97]
	ds_read_b64_tr_b16 v[122:123], v229 offset:29696
	ds_read_b64_tr_b16 v[124:125], v229 offset:30208
	v_mfma_f32_32x32x16_bf16 v[66:81], v[138:141], v[170:173], v[66:81]
	v_add_f32_e32 v130, v128, v130
	v_add_f32_e32 v130, v129, v130
	v_add_f32_e32 v130, v98, v130
	v_add_f32_e32 v130, v99, v130
	v_cvt_pk_bf16_f32 v160, v126, v127
	v_cvt_pk_bf16_f32 v161, v128, v129
	ds_read_b64_tr_b16 v[126:127], v229 offset:26624
	ds_read_b64_tr_b16 v[128:129], v229 offset:27136
	v_add_f32_e32 v130, v100, v130
	v_add_f32_e32 v130, v101, v130
	v_add_f32_e32 v130, v102, v130
	v_add_f32_e32 v130, v103, v130
	v_cvt_pk_bf16_f32 v150, v98, v99
	v_cvt_pk_bf16_f32 v151, v100, v101
	v_mfma_f32_32x32x16_bf16 v[82:97], v[142:145], v[162:165], v[82:97]
	ds_read_b64_tr_b16 v[98:99], v229 offset:30720
	ds_read_b64_tr_b16 v[100:101], v229 offset:31232
	v_mfma_f32_32x32x16_bf16 v[66:81], v[180:183], v[162:165], v[66:81]
	v_add_f32_e32 v130, v104, v130
	v_add_f32_e32 v130, v105, v130
	v_add_f32_e32 v130, v106, v130
	v_add_f32_e32 v130, v107, v130
	v_cvt_pk_bf16_f32 v152, v102, v103
	v_cvt_pk_bf16_f32 v153, v104, v105
	ds_read_b64_tr_b16 v[102:103], v229 offset:27648
	ds_read_b64_tr_b16 v[104:105], v229 offset:28160
	v_add_f32_e32 v130, v108, v130
	v_add_f32_e32 v130, v109, v130
	v_add_f32_e32 v130, v110, v130
	v_add_f32_e32 v130, v111, v130
	v_cvt_pk_bf16_f32 v146, v106, v107
	v_cvt_pk_bf16_f32 v147, v108, v109
	v_mfma_f32_32x32x16_bf16 v[82:97], v[184:187], v[154:157], v[82:97]
	ds_read_b64_tr_b16 v[106:107], v229 offset:31744
	ds_read_b64_tr_b16 v[108:109], v229 offset:32256
	v_mfma_f32_32x32x16_bf16 v[66:81], v[220:223], v[154:157], v[66:81]
	v_add_f32_e32 v130, v112, v130
	v_add_f32_e32 v130, v113, v130
	v_add_f32_e32 v179, 0, v130
	v_cvt_pk_bf16_f32 v148, v110, v111
	v_cvt_pk_bf16_f32 v149, v112, v113
	v_lshl_add_u64 v[110:111], v[214:215], 0, s[22:23]
	s_add_i32 s28, s6, 0x2000
	s_mov_b32 s29, m0
	s_mov_b32 m0, s28
	s_nop 0
	global_load_lds_dwordx4 v[110:111], off
	s_mov_b32 m0, s29
	v_lshl_add_u64 v[110:111], v[216:217], 0, s[24:25]
	s_add_i32 s6, s6, 0xa000
	s_mov_b32 s28, m0
	s_mov_b32 m0, s6
	s_nop 0
	global_load_lds_dwordx4 v[110:111], off
	s_mov_b32 m0, s28
	s_waitcnt lgkmcnt(14)
	v_mfma_f32_32x32x16_bf16 v[34:49], v[166:169], v[240:243], v[34:49]
	v_exp_f32_e32 v82, v82
	v_exp_f32_e32 v83, v83
	v_exp_f32_e32 v84, v84
	v_exp_f32_e32 v85, v85
	s_waitcnt lgkmcnt(12)
	v_mfma_f32_32x32x16_bf16 v[50:65], v[166:169], v[114:117], v[50:65]
	v_exp_f32_e32 v86, v86
	v_exp_f32_e32 v87, v87
	v_exp_f32_e32 v88, v88
	v_exp_f32_e32 v89, v89
	ds_read_b128 v[110:113], v228 offset:16384
	ds_read_b128 v[114:117], v228 offset:16896
	s_waitcnt lgkmcnt(12)
	v_mfma_f32_32x32x16_bf16 v[34:49], v[158:161], v[118:121], v[34:49]
	v_exp_f32_e32 v90, v90
	v_exp_f32_e32 v91, v91
	v_exp_f32_e32 v92, v92
	v_exp_f32_e32 v93, v93
	ds_read_b128 v[118:121], v228 offset:18432
	ds_read_b128 v[180:183], v228 offset:18944
	s_waitcnt lgkmcnt(12)
	v_mfma_f32_32x32x16_bf16 v[50:65], v[158:161], v[122:125], v[50:65]
	v_exp_f32_e32 v94, v94
	v_exp_f32_e32 v95, v95
	v_exp_f32_e32 v96, v96
	v_exp_f32_e32 v97, v97
	ds_read_b128 v[122:125], v228 offset:20480
	ds_read_b128 v[184:187], v228 offset:20992
	s_waitcnt lgkmcnt(12)
	v_mfma_f32_32x32x16_bf16 v[34:49], v[150:153], v[126:129], v[34:49]
	v_exp_f32_e32 v66, v66
	v_exp_f32_e32 v67, v67
	v_exp_f32_e32 v68, v68
	v_exp_f32_e32 v69, v69
	ds_read_b128 v[126:129], v228 offset:22528
	ds_read_b128 v[220:223], v228 offset:23040
	s_waitcnt lgkmcnt(12)
	v_mfma_f32_32x32x16_bf16 v[50:65], v[150:153], v[98:101], v[50:65]
	v_exp_f32_e32 v70, v70
	v_exp_f32_e32 v71, v71
	v_exp_f32_e32 v72, v72
	v_exp_f32_e32 v73, v73
	s_waitcnt lgkmcnt(10)
	v_mfma_f32_32x32x16_bf16 v[34:49], v[146:149], v[102:105], v[34:49]
	v_exp_f32_e32 v74, v74
	v_exp_f32_e32 v75, v75
	v_exp_f32_e32 v76, v76
	v_exp_f32_e32 v77, v77
	s_waitcnt lgkmcnt(8)
	v_mfma_f32_32x32x16_bf16 v[50:65], v[146:149], v[106:109], v[50:65]
	v_exp_f32_e32 v78, v78
	v_exp_f32_e32 v79, v79
	v_exp_f32_e32 v80, v80
	v_exp_f32_e32 v81, v81
	s_waitcnt vmcnt(2) lgkmcnt(0)
	s_barrier
	ds_read_b64_tr_b16 v[240:241], v229 offset:32768
	ds_read_b64_tr_b16 v[242:243], v229 offset:33280
	v_add_f32_e32 v98, v82, v83
	v_add_f32_e32 v98, v84, v98
	v_add_f32_e32 v98, v85, v98
	v_add_f32_e32 v98, v86, v98
	v_add_f32_e32 v98, v87, v98
	v_cvt_pk_bf16_f32 v166, v82, v83
	v_cvt_pk_bf16_f32 v167, v84, v85
	v_mfma_f32_32x32x16_bf16 v[130:145], v[110:113], v[174:177], v[18:33]
	ds_read_b64_tr_b16 v[82:83], v229 offset:36864
	ds_read_b64_tr_b16 v[84:85], v229 offset:37376
	v_add_f32_e32 v98, v88, v98
	v_add_f32_e32 v98, v89, v98
	v_add_f32_e32 v98, v90, v98
	v_add_f32_e32 v146, v91, v98
	v_mfma_f32_32x32x16_bf16 v[98:113], v[114:117], v[174:177], v[18:33]
	v_cvt_pk_bf16_f32 v168, v86, v87
	v_cvt_pk_bf16_f32 v169, v88, v89
	ds_read_b64_tr_b16 v[86:87], v229 offset:33792
	ds_read_b64_tr_b16 v[88:89], v229 offset:34304
	v_add_f32_e32 v114, v92, v146
	v_add_f32_e32 v114, v93, v114
	v_add_f32_e32 v114, v94, v114
	v_add_f32_e32 v114, v95, v114
	v_cvt_pk_bf16_f32 v158, v90, v91
	v_cvt_pk_bf16_f32 v159, v92, v93
	v_mfma_f32_32x32x16_bf16 v[130:145], v[118:121], v[170:173], v[130:145]
	ds_read_b64_tr_b16 v[90:91], v229 offset:37888
	ds_read_b64_tr_b16 v[92:93], v229 offset:38400
	v_mfma_f32_32x32x16_bf16 v[98:113], v[180:183], v[170:173], v[98:113]
	v_add_f32_e32 v114, v96, v114
	v_add_f32_e32 v114, v97, v114
	v_add_f32_e32 v114, v66, v114
	v_add_f32_e32 v114, v67, v114
	v_cvt_pk_bf16_f32 v160, v94, v95
	v_cvt_pk_bf16_f32 v161, v96, v97
	ds_read_b64_tr_b16 v[94:95], v229 offset:34816
	ds_read_b64_tr_b16 v[96:97], v229 offset:35328
	v_add_f32_e32 v114, v68, v114
	v_add_f32_e32 v114, v69, v114
	v_add_f32_e32 v114, v70, v114
	v_add_f32_e32 v114, v71, v114
	v_cvt_pk_bf16_f32 v150, v66, v67
	v_cvt_pk_bf16_f32 v151, v68, v69
	v_mfma_f32_32x32x16_bf16 v[130:145], v[122:125], v[162:165], v[130:145]
	ds_read_b64_tr_b16 v[66:67], v229 offset:38912
	ds_read_b64_tr_b16 v[68:69], v229 offset:39424
	v_mfma_f32_32x32x16_bf16 v[98:113], v[184:187], v[162:165], v[98:113]
	v_add_f32_e32 v114, v72, v114
	v_add_f32_e32 v114, v73, v114
	v_add_f32_e32 v114, v74, v114
	v_add_f32_e32 v114, v75, v114
	v_cvt_pk_bf16_f32 v152, v70, v71
	v_cvt_pk_bf16_f32 v153, v72, v73
	ds_read_b64_tr_b16 v[70:71], v229 offset:35840
	ds_read_b64_tr_b16 v[72:73], v229 offset:36352
	v_add_f32_e32 v114, v76, v114
	v_add_f32_e32 v114, v77, v114
	v_add_f32_e32 v114, v78, v114
	v_add_f32_e32 v114, v79, v114
	v_cvt_pk_bf16_f32 v146, v74, v75
	v_cvt_pk_bf16_f32 v147, v76, v77
	v_mfma_f32_32x32x16_bf16 v[130:145], v[126:129], v[154:157], v[130:145]
	ds_read_b64_tr_b16 v[74:75], v229 offset:39936
	ds_read_b64_tr_b16 v[76:77], v229 offset:40448
	v_mfma_f32_32x32x16_bf16 v[98:113], v[220:223], v[154:157], v[98:113]
	v_add_f32_e32 v114, v80, v114
	v_add_f32_e32 v114, v81, v114
	v_add_f32_e32 v180, 0, v114
	v_cvt_pk_bf16_f32 v148, v78, v79
	v_cvt_pk_bf16_f32 v149, v80, v81
	v_lshl_add_u64 v[78:79], v[216:217], 0, s[16:17]
	s_mov_b32 s6, m0
	s_mov_b32 m0, s58
	s_nop 0
	global_load_lds_dwordx4 v[78:79], off
	s_mov_b32 m0, s6
	s_waitcnt lgkmcnt(14)
	v_mfma_f32_32x32x16_bf16 v[34:49], v[166:169], v[240:243], v[34:49]
	s_nop 0
	v_exp_f32_e32 v130, v130
	v_exp_f32_e32 v131, v131
	v_exp_f32_e32 v132, v132
	v_exp_f32_e32 v133, v133
	s_waitcnt lgkmcnt(12)
	v_mfma_f32_32x32x16_bf16 v[50:65], v[166:169], v[82:85], v[50:65]
	v_exp_f32_e32 v134, v134
	v_exp_f32_e32 v135, v135
	v_exp_f32_e32 v136, v136
	v_exp_f32_e32 v137, v137
	ds_read_b128 v[78:81], v228
	ds_read_b128 v[182:185], v228 offset:512
	s_waitcnt lgkmcnt(12)
	v_mfma_f32_32x32x16_bf16 v[34:49], v[158:161], v[86:89], v[34:49]
	v_exp_f32_e32 v138, v138
	v_exp_f32_e32 v139, v139
	v_exp_f32_e32 v140, v140
	v_exp_f32_e32 v141, v141
	ds_read_b128 v[186:189], v228 offset:2048
	ds_read_b128 v[220:223], v228 offset:2560
	s_waitcnt lgkmcnt(12)
	v_mfma_f32_32x32x16_bf16 v[50:65], v[158:161], v[90:93], v[50:65]
	v_exp_f32_e32 v142, v142
	v_exp_f32_e32 v143, v143
	v_exp_f32_e32 v144, v144
	v_exp_f32_e32 v145, v145
	ds_read_b128 v[240:243], v228 offset:4096
	ds_read_b128 v[244:247], v228 offset:4608
	s_waitcnt lgkmcnt(12)
	v_mfma_f32_32x32x16_bf16 v[34:49], v[150:153], v[94:97], v[34:49]
	v_exp_f32_e32 v98, v98
	v_exp_f32_e32 v99, v99
	v_exp_f32_e32 v100, v100
	v_exp_f32_e32 v101, v101
	ds_read_b128 v[248:251], v228 offset:6144
	ds_read_b128 v[224:227], v228 offset:6656
	s_waitcnt lgkmcnt(12)
	v_mfma_f32_32x32x16_bf16 v[50:65], v[150:153], v[66:69], v[50:65]
	v_exp_f32_e32 v102, v102
	v_exp_f32_e32 v103, v103
	v_exp_f32_e32 v104, v104
	v_exp_f32_e32 v105, v105
	s_waitcnt lgkmcnt(10)
	v_mfma_f32_32x32x16_bf16 v[34:49], v[146:149], v[70:73], v[34:49]
	v_exp_f32_e32 v106, v106
	v_exp_f32_e32 v107, v107
	v_exp_f32_e32 v108, v108
	v_exp_f32_e32 v109, v109
	s_waitcnt lgkmcnt(8)
	v_mfma_f32_32x32x16_bf16 v[50:65], v[146:149], v[74:77], v[50:65]
	v_exp_f32_e32 v110, v110
	v_exp_f32_e32 v111, v111
	v_exp_f32_e32 v112, v112
	v_exp_f32_e32 v113, v113
	s_waitcnt vmcnt(1) lgkmcnt(0)
	s_barrier
	ds_read_b64_tr_b16 v[66:67], v229 offset:40960
	ds_read_b64_tr_b16 v[68:69], v229 offset:41472
	v_add_f32_e32 v70, v130, v131
	v_add_f32_e32 v70, v132, v70
	v_add_f32_e32 v70, v133, v70
	v_add_f32_e32 v70, v134, v70
	v_add_f32_e32 v74, v135, v70
	v_cvt_pk_bf16_f32 v166, v130, v131
	v_cvt_pk_bf16_f32 v167, v132, v133
	v_mfma_f32_32x32x16_bf16 v[114:129], v[78:81], v[174:177], v[18:33]
	ds_read_b64_tr_b16 v[70:71], v229 offset:45056
	ds_read_b64_tr_b16 v[72:73], v229 offset:45568
	v_add_f32_e32 v74, v136, v74
	v_add_f32_e32 v74, v137, v74
	v_add_f32_e32 v74, v138, v74
	v_add_f32_e32 v78, v139, v74
	v_cvt_pk_bf16_f32 v168, v134, v135
	v_cvt_pk_bf16_f32 v169, v136, v137
	v_mfma_f32_32x32x16_bf16 v[82:97], v[182:185], v[174:177], v[18:33]
	ds_read_b64_tr_b16 v[74:75], v229 offset:41984
	ds_read_b64_tr_b16 v[76:77], v229 offset:42496
	v_add_f32_e32 v78, v140, v78
	v_add_f32_e32 v78, v141, v78
	v_add_f32_e32 v78, v142, v78
	v_add_f32_e32 v130, v143, v78
	v_cvt_pk_bf16_f32 v158, v138, v139
	v_cvt_pk_bf16_f32 v159, v140, v141
	v_mfma_f32_32x32x16_bf16 v[114:129], v[186:189], v[170:173], v[114:129]
	ds_read_b64_tr_b16 v[78:79], v229 offset:46080
	ds_read_b64_tr_b16 v[80:81], v229 offset:46592
	v_add_f32_e32 v130, v144, v130
	v_add_f32_e32 v130, v145, v130
	v_add_f32_e32 v130, v98, v130
	v_add_f32_e32 v134, v99, v130
	v_cvt_pk_bf16_f32 v160, v142, v143
	v_cvt_pk_bf16_f32 v161, v144, v145
	v_mfma_f32_32x32x16_bf16 v[82:97], v[220:223], v[170:173], v[82:97]
	ds_read_b64_tr_b16 v[130:131], v229 offset:43008
	ds_read_b64_tr_b16 v[132:133], v229 offset:43520
	v_add_f32_e32 v134, v100, v134
	v_add_f32_e32 v134, v101, v134
	v_add_f32_e32 v134, v102, v134
	v_add_f32_e32 v138, v103, v134
	v_cvt_pk_bf16_f32 v150, v98, v99
	v_cvt_pk_bf16_f32 v151, v100, v101
	v_mfma_f32_32x32x16_bf16 v[114:129], v[240:243], v[162:165], v[114:129]
	ds_read_b64_tr_b16 v[134:135], v229 offset:47104
	ds_read_b64_tr_b16 v[136:137], v229 offset:47616
	v_add_f32_e32 v98, v104, v138
	v_add_f32_e32 v98, v105, v98
	v_add_f32_e32 v98, v106, v98
	v_add_f32_e32 v98, v107, v98
	v_cvt_pk_bf16_f32 v152, v102, v103
	v_cvt_pk_bf16_f32 v153, v104, v105
	v_mfma_f32_32x32x16_bf16 v[82:97], v[244:247], v[162:165], v[82:97]
	ds_read_b64_tr_b16 v[100:101], v229 offset:44032
	ds_read_b64_tr_b16 v[102:103], v229 offset:44544
	v_add_f32_e32 v98, v108, v98
	v_add_f32_e32 v98, v109, v98
	v_add_f32_e32 v98, v110, v98
	v_add_f32_e32 v98, v111, v98
	v_cvt_pk_bf16_f32 v146, v106, v107
	v_cvt_pk_bf16_f32 v147, v108, v109
	v_mfma_f32_32x32x16_bf16 v[114:129], v[248:251], v[154:157], v[114:129]
	ds_read_b64_tr_b16 v[104:105], v229 offset:48128
	ds_read_b64_tr_b16 v[106:107], v229 offset:48640
	v_add_f32_e32 v98, v112, v98
	v_add_f32_e32 v98, v113, v98
	v_add_f32_e32 v98, 0, v98
	v_cvt_pk_bf16_f32 v148, v110, v111
	v_cvt_pk_bf16_f32 v149, v112, v113
	v_mfma_f32_32x32x16_bf16 v[82:97], v[224:227], v[154:157], v[82:97]
	v_lshl_add_u64 v[108:109], v[216:217], 0, s[22:23]
	s_mov_b32 s6, m0
	s_mov_b32 m0, s2
	s_nop 0
	global_load_lds_dwordx4 v[108:109], off
	s_mov_b32 m0, s6
	s_waitcnt lgkmcnt(14)
	v_mfma_f32_32x32x16_bf16 v[34:49], v[166:169], v[66:69], v[34:49]
	s_nop 0
	v_exp_f32_e32 v114, v114
	v_exp_f32_e32 v115, v115
	v_exp_f32_e32 v116, v116
	v_exp_f32_e32 v117, v117
	s_waitcnt lgkmcnt(12)
	v_mfma_f32_32x32x16_bf16 v[50:65], v[166:169], v[70:73], v[50:65]
	v_exp_f32_e32 v118, v118
	v_exp_f32_e32 v119, v119
	v_exp_f32_e32 v120, v120
	v_exp_f32_e32 v121, v121
	ds_read_b128 v[108:111], v228 offset:8192
	ds_read_b128 v[138:141], v228 offset:8704
	s_waitcnt lgkmcnt(12)
	v_mfma_f32_32x32x16_bf16 v[34:49], v[158:161], v[74:77], v[34:49]
	v_exp_f32_e32 v122, v122
	v_exp_f32_e32 v123, v123
	v_exp_f32_e32 v124, v124
	v_exp_f32_e32 v125, v125
	ds_read_b128 v[142:145], v228 offset:10240
	ds_read_b128 v[182:185], v228 offset:10752
	s_waitcnt lgkmcnt(12)
	v_mfma_f32_32x32x16_bf16 v[50:65], v[158:161], v[78:81], v[50:65]
	v_exp_f32_e32 v126, v126
	v_exp_f32_e32 v127, v127
	v_exp_f32_e32 v128, v128
	v_exp_f32_e32 v129, v129
	ds_read_b128 v[186:189], v228 offset:12288
	ds_read_b128 v[220:223], v228 offset:12800
	s_waitcnt lgkmcnt(12)
	v_mfma_f32_32x32x16_bf16 v[34:49], v[150:153], v[130:133], v[34:49]
	v_exp_f32_e32 v82, v82
	v_exp_f32_e32 v83, v83
	v_exp_f32_e32 v84, v84
	v_exp_f32_e32 v85, v85
	ds_read_b128 v[130:133], v228 offset:14336
	ds_read_b128 v[224:227], v228 offset:14848
	s_waitcnt lgkmcnt(12)
	v_mfma_f32_32x32x16_bf16 v[50:65], v[150:153], v[134:137], v[50:65]
	v_exp_f32_e32 v86, v86
	v_exp_f32_e32 v87, v87
	v_exp_f32_e32 v88, v88
	v_exp_f32_e32 v89, v89
	s_waitcnt lgkmcnt(10)
	v_mfma_f32_32x32x16_bf16 v[34:49], v[146:149], v[100:103], v[34:49]
	v_exp_f32_e32 v90, v90
	v_exp_f32_e32 v91, v91
	v_exp_f32_e32 v92, v92
	v_exp_f32_e32 v93, v93
	s_waitcnt lgkmcnt(8)
	v_mfma_f32_32x32x16_bf16 v[50:65], v[146:149], v[104:107], v[50:65]
	v_exp_f32_e32 v94, v94
	v_exp_f32_e32 v95, v95
	v_exp_f32_e32 v96, v96
	v_exp_f32_e32 v97, v97
	s_waitcnt vmcnt(0) lgkmcnt(0)
	s_barrier
	ds_read_b64_tr_b16 v[100:101], v229 offset:24576
	ds_read_b64_tr_b16 v[102:103], v229 offset:25088
	v_add_f32_e32 v66, v114, v115
	v_add_f32_e32 v66, v116, v66
	v_add_f32_e32 v66, v117, v66
	v_add_f32_e32 v66, v118, v66
	v_add_f32_e32 v99, v119, v66
	v_mfma_f32_32x32x16_bf16 v[66:81], v[108:111], v[174:177], v[18:33]
	v_cvt_pk_bf16_f32 v166, v114, v115
	v_cvt_pk_bf16_f32 v167, v116, v117
	ds_read_b64_tr_b16 v[104:105], v229 offset:28672
	ds_read_b64_tr_b16 v[106:107], v229 offset:29184
	v_mfma_f32_32x32x16_bf16 v[18:33], v[138:141], v[174:177], v[18:33]
	v_add_f32_e32 v99, v120, v99
	v_add_f32_e32 v99, v121, v99
	v_add_f32_e32 v99, v122, v99
	v_add_f32_e32 v99, v123, v99
	v_cvt_pk_bf16_f32 v168, v118, v119
	v_cvt_pk_bf16_f32 v169, v120, v121
	ds_read_b64_tr_b16 v[108:109], v229 offset:25600
	ds_read_b64_tr_b16 v[110:111], v229 offset:26112
	v_mfma_f32_32x32x16_bf16 v[66:81], v[142:145], v[170:173], v[66:81]
	v_add_f32_e32 v99, v124, v99
	v_add_f32_e32 v99, v125, v99
	v_add_f32_e32 v99, v126, v99
	v_add_f32_e32 v99, v127, v99
	v_cvt_pk_bf16_f32 v158, v122, v123
	v_cvt_pk_bf16_f32 v159, v124, v125
	ds_read_b64_tr_b16 v[112:113], v229 offset:29696
	ds_read_b64_tr_b16 v[114:115], v229 offset:30208
	v_mfma_f32_32x32x16_bf16 v[18:33], v[182:185], v[170:173], v[18:33]
	v_add_f32_e32 v99, v128, v99
	v_add_f32_e32 v99, v129, v99
	v_add_f32_e32 v99, v82, v99
	v_add_f32_e32 v99, v83, v99
	v_cvt_pk_bf16_f32 v160, v126, v127
	v_cvt_pk_bf16_f32 v161, v128, v129
	ds_read_b64_tr_b16 v[116:117], v229 offset:26624
	ds_read_b64_tr_b16 v[118:119], v229 offset:27136
	v_mfma_f32_32x32x16_bf16 v[66:81], v[186:189], v[162:165], v[66:81]
	v_add_f32_e32 v99, v84, v99
	v_add_f32_e32 v99, v85, v99
	v_add_f32_e32 v99, v86, v99
	v_add_f32_e32 v99, v87, v99
	v_cvt_pk_bf16_f32 v150, v82, v83
	v_cvt_pk_bf16_f32 v151, v84, v85
	ds_read_b64_tr_b16 v[82:83], v229 offset:30720
	ds_read_b64_tr_b16 v[84:85], v229 offset:31232
	v_mfma_f32_32x32x16_bf16 v[18:33], v[220:223], v[162:165], v[18:33]
	v_add_f32_e32 v99, v88, v99
	v_add_f32_e32 v99, v89, v99
	v_add_f32_e32 v99, v90, v99
	v_add_f32_e32 v99, v91, v99
	v_cvt_pk_bf16_f32 v152, v86, v87
	v_cvt_pk_bf16_f32 v153, v88, v89
	ds_read_b64_tr_b16 v[86:87], v229 offset:27648
	ds_read_b64_tr_b16 v[88:89], v229 offset:28160
	v_mfma_f32_32x32x16_bf16 v[66:81], v[130:133], v[154:157], v[66:81]
	v_add_f32_e32 v99, v92, v99
	v_add_f32_e32 v99, v93, v99
	v_add_f32_e32 v99, v94, v99
	v_add_f32_e32 v99, v95, v99
	v_cvt_pk_bf16_f32 v146, v90, v91
	v_cvt_pk_bf16_f32 v147, v92, v93
	ds_read_b64_tr_b16 v[90:91], v229 offset:31744
	ds_read_b64_tr_b16 v[92:93], v229 offset:32256
	v_mfma_f32_32x32x16_bf16 v[18:33], v[224:227], v[154:157], v[18:33]
	v_add_f32_e32 v99, v96, v99
	v_add_f32_e32 v99, v97, v99
	v_add_f32_e32 v99, 0, v99
	v_cvt_pk_bf16_f32 v148, v94, v95
	v_cvt_pk_bf16_f32 v149, v96, v97
	s_mov_b32 s101, 0
	s_cmp_lt_i32 s53, s0
	s_cbranch_scc0 .Lqpf_skip
	s_add_i32 s100, s53, s1
	s_cmpk_gt_i32 s100, 0x3ff
	s_cbranch_scc1 .Lqpf_skip
	s_lshr_b32 s98, s100, 6
	s_lshl_b32 s98, s98, 11
	s_and_b32 s99, s100, 7
	s_lshl_b32 s99, s99, 8
	s_add_i32 s98, s98, s99
	s_lshl_b32 s99, s55, 5
	s_add_i32 s98, s98, s99
	s_lshl_b32 s98, s98, 10
	s_bfe_u32 s99, s100, 0x30003
	s_lshl_b32 s99, s99, 7
	s_add_i32 s98, s98, s99
	s_add_u32 s98, s33, s98
	s_addc_u32 s99, s34, 0
	global_load_dwordx4 v[174:177], v238, s[98:99] nt
	global_load_dwordx4 v[170:173], v238, s[98:99] offset:32 nt
	global_load_dwordx4 v[162:165], v238, s[98:99] offset:64 nt
	global_load_dwordx4 v[154:157], v238, s[98:99] offset:96 nt
	s_mov_b32 s101, 1

.LBB0_767:
	s_lshl_b32 s66, s26, 8
	s_lshl_b32 s91, s28, 4
	v_lshl_or_b32 v210, s30, 8, v216
	s_add_i32 s8, s66, s91
	s_ashr_i32 s9, s8, 31
	v_ashrrev_i32_e32 v211, 31, v210
	v_lshl_add_u64 v[130:131], v[210:211], 2, s[18:19]
	s_lshl_b64 s[64:65], s[8:9], 10
	s_lshl_b64 s[8:9], s[8:9], 12
	v_lshl_add_u64 v[132:133], v[130:131], 0, s[8:9]
	s_or_b32 s62, s64, 0x400
	s_mov_b32 s63, s65
	s_or_b32 s60, s64, 0x800
	s_mov_b32 s61, s65
	s_barrier
	v_lshl_add_u64 v[134:135], s[62:63], 2, v[130:131]
	global_load_dwordx4 v[190:193], v[132:133], off nt
	global_load_dwordx4 v[182:185], v[134:135], off nt
	v_lshl_add_u64 v[132:133], s[60:61], 2, v[130:131]
	s_or_b32 s58, s64, 0xc00
	s_mov_b32 s59, s65
	s_or_b32 s56, s64, 0x1000
	s_mov_b32 s57, s65
	v_lshl_add_u64 v[134:135], s[58:59], 2, v[130:131]
	global_load_dwordx4 v[186:189], v[132:133], off nt
	global_load_dwordx4 v[178:181], v[134:135], off nt
	v_lshl_add_u64 v[132:133], s[56:57], 2, v[130:131]
	s_or_b32 s54, s64, 0x1400
	s_mov_b32 s55, s65
	s_or_b32 s52, s64, 0x1800
	s_mov_b32 s53, s65
	v_lshl_add_u64 v[134:135], s[54:55], 2, v[130:131]
	global_load_dwordx4 v[174:177], v[132:133], off nt
	global_load_dwordx4 v[170:173], v[134:135], off nt
	v_lshl_add_u64 v[132:133], s[52:53], 2, v[130:131]
	s_or_b32 s46, s64, 0x1c00
	s_mov_b32 s47, s65
	s_or_b32 s42, s64, 0x2000
	s_mov_b32 s43, s65
	v_lshl_add_u64 v[134:135], s[46:47], 2, v[130:131]
	global_load_dwordx4 v[166:169], v[132:133], off nt
	global_load_dwordx4 v[162:165], v[134:135], off nt
	v_lshl_add_u64 v[132:133], s[42:43], 2, v[130:131]
	s_or_b32 s44, s64, 0x2400
	s_mov_b32 s45, s65
	s_or_b32 s48, s64, 0x2800
	s_mov_b32 s49, s65
	v_lshl_add_u64 v[134:135], s[44:45], 2, v[130:131]
	global_load_dwordx4 v[158:161], v[132:133], off nt
	global_load_dwordx4 v[154:157], v[134:135], off nt
	v_lshl_add_u64 v[132:133], s[48:49], 2, v[130:131]
	s_or_b32 s50, s64, 0x2c00
	s_mov_b32 s51, s65
	s_or_b32 s40, s64, 0x3000
	s_mov_b32 s41, s65
	v_lshl_add_u64 v[134:135], s[50:51], 2, v[130:131]
	global_load_dwordx4 v[150:153], v[132:133], off nt
	global_load_dwordx4 v[146:149], v[134:135], off nt
	v_lshl_add_u64 v[132:133], s[40:41], 2, v[130:131]
	s_or_b32 s38, s64, 0x3400
	s_mov_b32 s39, s65
	s_or_b32 s36, s64, 0x3800
	s_mov_b32 s37, s65
	s_or_b32 s34, s64, 0x3c00
	s_mov_b32 s35, s65
	v_lshl_add_u64 v[134:135], s[38:39], 2, v[130:131]
	global_load_dwordx4 v[142:145], v[132:133], off nt
	global_load_dwordx4 v[138:141], v[134:135], off nt
	v_lshl_add_u64 v[132:133], s[36:37], 2, v[130:131]
	v_lshl_add_u64 v[130:131], s[34:35], 2, v[130:131]
	global_load_dwordx4 v[134:137], v[132:133], off nt
	s_nop 0
	global_load_dwordx4 v[130:133], v[130:131], off nt
	v_mul_f32_e32 v213, v127, v127
	v_mul_f32_e32 v214, v129, v129
	v_fmac_f32_e32 v213, v126, v126
	v_fmac_f32_e32 v214, v128, v128
	v_add_f32_e32 v213, v213, v214
	v_mul_f32_e32 v214, v123, v123
	v_mul_f32_e32 v215, v125, v125
	v_fmac_f32_e32 v214, v122, v122
	v_fmac_f32_e32 v215, v124, v124
	v_add_f32_e32 v214, v214, v215
	v_add_f32_e32 v213, v213, v214
	v_mul_f32_e32 v214, v103, v103
	v_mul_f32_e32 v215, v105, v105
	v_fmac_f32_e32 v214, v102, v102
	v_fmac_f32_e32 v215, v104, v104
	v_and_b32_e32 v212, 64, v227
	v_add_f32_e32 v214, v214, v215
	v_xor_b32_e32 v194, 16, v227
	v_add_u32_e32 v212, 64, v212
	v_add_f32_e32 v213, v213, v214
	v_mul_f32_e32 v214, v95, v95
	v_mul_f32_e32 v215, v97, v97
	v_cmp_lt_i32_e32 vcc, v194, v212
	v_fmac_f32_e32 v214, v94, v94
	v_fmac_f32_e32 v215, v96, v96
	v_cndmask_b32_e32 v194, v227, v194, vcc
	v_add_f32_e32 v214, v214, v215
	v_lshlrev_b32_e32 v194, 2, v194
	v_add_f32_e32 v213, v213, v214
	v_mov_b32_e32 v214, v213
	s_nop 1
	v_permlane16_swap_b32_e32 v213, v214
	v_xor_b32_e32 v215, 32, v227
	v_cmp_lt_i32_e32 vcc, v215, v212
	s_lshl_b32 s8, s27, 2
	s_add_i32 s67, s8, 0
	v_cndmask_b32_e32 v212, v227, v215, vcc
	v_lshlrev_b32_e32 v212, 2, v212
	s_waitcnt lgkmcnt(0)
	v_add_f32_e32 v213, v213, v214
	v_mov_b32_e32 v214, v213
	s_nop 1
	v_permlane32_swap_b32_e32 v213, v214
	s_add_i32 s67, s67, 0x20800
	s_and_saveexec_b64 s[8:9], s[0:1]
	s_cbranch_execz .LBB0_769
	s_lshl_b32 s68, s2, 10
	s_add_i32 s68, s67, s68
	v_add_u32_e32 v215, s68, v223
	s_waitcnt lgkmcnt(0)
	v_add_f32_e32 v213, v213, v214
	ds_write_b32 v215, v213
.LBB0_769:
	s_or_b64 exec, exec, s[8:9]
	v_mul_f32_e32 v213, v119, v119
	s_waitcnt lgkmcnt(0)
	v_mul_f32_e32 v214, v121, v121
	v_fmac_f32_e32 v213, v118, v118
	v_fmac_f32_e32 v214, v120, v120
	v_add_f32_e32 v213, v213, v214
	v_mul_f32_e32 v214, v115, v115
	v_mul_f32_e32 v215, v117, v117
	v_fmac_f32_e32 v214, v114, v114
	v_fmac_f32_e32 v215, v116, v116
	v_add_f32_e32 v214, v214, v215
	v_add_f32_e32 v213, v213, v214
	v_mul_f32_e32 v214, v87, v87
	v_mul_f32_e32 v215, v89, v89
	v_fmac_f32_e32 v214, v86, v86
	v_fmac_f32_e32 v215, v88, v88
	v_add_f32_e32 v214, v214, v215
	v_add_f32_e32 v213, v213, v214
	v_mul_f32_e32 v214, v83, v83
	v_mul_f32_e32 v215, v85, v85
	v_fmac_f32_e32 v214, v82, v82
	v_fmac_f32_e32 v215, v84, v84
	v_add_f32_e32 v214, v214, v215
	v_add_f32_e32 v213, v213, v214
	v_mov_b32_e32 v214, v213
	s_nop 1
	v_permlane16_swap_b32_e32 v213, v214
	s_waitcnt lgkmcnt(0)
	v_add_f32_e32 v213, v213, v214
	v_mov_b32_e32 v214, v213
	s_nop 1
	v_permlane32_swap_b32_e32 v213, v214
	s_and_saveexec_b64 s[8:9], s[0:1]
	s_cbranch_execz .LBB0_771
	s_lshl_b32 s68, s2, 10
	s_add_i32 s68, s67, s68
	v_add_u32_e32 v215, s68, v223
	s_waitcnt lgkmcnt(0)
	v_add_f32_e32 v213, v213, v214
	ds_write_b32 v215, v213 offset:256
.LBB0_771:
	s_or_b64 exec, exec, s[8:9]
	v_mul_f32_e32 v213, v111, v111
	s_waitcnt lgkmcnt(0)
	v_mul_f32_e32 v214, v113, v113
	v_fmac_f32_e32 v213, v110, v110
	v_fmac_f32_e32 v214, v112, v112
	v_add_f32_e32 v213, v213, v214
	v_mul_f32_e32 v214, v107, v107
	v_mul_f32_e32 v215, v109, v109
	v_fmac_f32_e32 v214, v106, v106
	v_fmac_f32_e32 v215, v108, v108
	v_add_f32_e32 v214, v214, v215
	v_add_f32_e32 v213, v213, v214
	v_mul_f32_e32 v214, v79, v79
	v_mul_f32_e32 v215, v81, v81
	v_fmac_f32_e32 v214, v78, v78
	v_fmac_f32_e32 v215, v80, v80
	v_add_f32_e32 v214, v214, v215
	v_add_f32_e32 v213, v213, v214
	v_mul_f32_e32 v214, v75, v75
	v_mul_f32_e32 v215, v77, v77
	v_fmac_f32_e32 v214, v74, v74
	v_fmac_f32_e32 v215, v76, v76
	v_add_f32_e32 v214, v214, v215
	v_add_f32_e32 v213, v213, v214
	v_mov_b32_e32 v214, v213
	s_nop 1
	v_permlane16_swap_b32_e32 v213, v214
	s_waitcnt lgkmcnt(0)
	v_add_f32_e32 v213, v213, v214
	v_mov_b32_e32 v214, v213
	s_nop 1
	v_permlane32_swap_b32_e32 v213, v214
	s_and_saveexec_b64 s[8:9], s[0:1]
	s_cbranch_execz .LBB0_773
	s_lshl_b32 s68, s2, 10
	s_add_i32 s68, s67, s68
	v_add_u32_e32 v215, s68, v223
	s_waitcnt lgkmcnt(0)
	v_add_f32_e32 v213, v213, v214
	ds_write_b32 v215, v213 offset:512
.LBB0_773:
	s_or_b64 exec, exec, s[8:9]
	v_mul_f32_e32 v213, v99, v99
	s_waitcnt lgkmcnt(0)
	v_mul_f32_e32 v214, v101, v101
	v_fmac_f32_e32 v213, v98, v98
	v_fmac_f32_e32 v214, v100, v100
	v_add_f32_e32 v213, v213, v214
	v_mul_f32_e32 v214, v91, v91
	v_mul_f32_e32 v215, v93, v93
	v_fmac_f32_e32 v214, v90, v90
	v_fmac_f32_e32 v215, v92, v92
	v_add_f32_e32 v214, v214, v215
	v_add_f32_e32 v213, v213, v214
	v_mul_f32_e32 v214, v71, v71
	v_mul_f32_e32 v215, v73, v73
	v_fmac_f32_e32 v214, v70, v70
	v_fmac_f32_e32 v215, v72, v72
	v_add_f32_e32 v214, v214, v215
	v_add_f32_e32 v213, v213, v214
	v_mul_f32_e32 v214, v67, v67
	v_mul_f32_e32 v215, v69, v69
	v_fmac_f32_e32 v214, v66, v66
	v_fmac_f32_e32 v215, v68, v68
	v_add_f32_e32 v214, v214, v215
	v_add_f32_e32 v213, v213, v214
	v_mov_b32_e32 v214, v213
	s_nop 1
	v_permlane16_swap_b32_e32 v213, v214
	s_waitcnt lgkmcnt(0)
	v_add_f32_e32 v213, v213, v214
	v_mov_b32_e32 v214, v213
	s_nop 1
	v_permlane32_swap_b32_e32 v213, v214
	s_and_saveexec_b64 s[8:9], s[0:1]
	s_cbranch_execz .LBB0_775
	s_lshl_b32 s68, s2, 10
	s_add_i32 s68, s67, s68
	v_add_u32_e32 v215, s68, v223
	s_waitcnt lgkmcnt(0)
	v_add_f32_e32 v213, v213, v214
	ds_write_b32 v215, v213 offset:768
.LBB0_775:
	s_or_b64 exec, exec, s[8:9]
	v_mul_f32_e32 v213, v63, v63
	s_waitcnt lgkmcnt(0)
	v_mul_f32_e32 v214, v65, v65
	v_fmac_f32_e32 v213, v62, v62
	v_fmac_f32_e32 v214, v64, v64
	v_add_f32_e32 v213, v213, v214
	v_mul_f32_e32 v214, v59, v59
	v_mul_f32_e32 v215, v61, v61
	v_fmac_f32_e32 v214, v58, v58
	v_fmac_f32_e32 v215, v60, v60
	v_add_f32_e32 v214, v214, v215
	v_add_f32_e32 v213, v213, v214
	v_mul_f32_e32 v214, v39, v39
	v_mul_f32_e32 v215, v41, v41
	v_fmac_f32_e32 v214, v38, v38
	v_fmac_f32_e32 v215, v40, v40
	v_add_f32_e32 v214, v214, v215
	v_add_f32_e32 v213, v213, v214
	v_mul_f32_e32 v214, v31, v31
	v_mul_f32_e32 v215, v33, v33
	v_fmac_f32_e32 v214, v30, v30
	v_fmac_f32_e32 v215, v32, v32
	v_add_f32_e32 v214, v214, v215
	v_add_f32_e32 v213, v213, v214
	v_mov_b32_e32 v214, v213
	s_nop 1
	v_permlane16_swap_b32_e32 v213, v214
	s_waitcnt lgkmcnt(0)
	v_add_f32_e32 v213, v213, v214
	v_mov_b32_e32 v214, v213
	s_nop 1
	v_permlane32_swap_b32_e32 v213, v214
	s_and_saveexec_b64 s[8:9], s[0:1]
	s_cbranch_execz .LBB0_777
	s_lshl_b32 s68, s2, 10
	s_add_i32 s68, s67, s68
	v_add_u32_e32 v215, s68, v223
	s_waitcnt lgkmcnt(0)
	v_add_f32_e32 v213, v213, v214
	ds_write_b32 v215, v213 offset:2048
.LBB0_777:
	s_or_b64 exec, exec, s[8:9]
	v_mul_f32_e32 v213, v55, v55
	s_waitcnt lgkmcnt(0)
	v_mul_f32_e32 v214, v57, v57
	v_fmac_f32_e32 v213, v54, v54
	v_fmac_f32_e32 v214, v56, v56
	v_add_f32_e32 v213, v213, v214
	v_mul_f32_e32 v214, v51, v51
	v_mul_f32_e32 v215, v53, v53
	v_fmac_f32_e32 v214, v50, v50
	v_fmac_f32_e32 v215, v52, v52
	v_add_f32_e32 v214, v214, v215
	v_add_f32_e32 v213, v213, v214
	v_mul_f32_e32 v214, v23, v23
	v_mul_f32_e32 v215, v25, v25
	v_fmac_f32_e32 v214, v22, v22
	v_fmac_f32_e32 v215, v24, v24
	v_add_f32_e32 v214, v214, v215
	v_add_f32_e32 v213, v213, v214
	v_mul_f32_e32 v214, v19, v19
	v_mul_f32_e32 v215, v21, v21
	v_fmac_f32_e32 v214, v18, v18
	v_fmac_f32_e32 v215, v20, v20
	v_add_f32_e32 v214, v214, v215
	v_add_f32_e32 v213, v213, v214
	v_mov_b32_e32 v214, v213
	s_nop 1
	v_permlane16_swap_b32_e32 v213, v214
	s_waitcnt lgkmcnt(0)
	v_add_f32_e32 v213, v213, v214
	v_mov_b32_e32 v214, v213
	s_nop 1
	v_permlane32_swap_b32_e32 v213, v214
	s_and_saveexec_b64 s[8:9], s[0:1]
	s_cbranch_execz .LBB0_779
	s_lshl_b32 s68, s2, 10
	s_add_i32 s68, s67, s68
	v_add_u32_e32 v215, s68, v223
	s_waitcnt lgkmcnt(0)
	v_add_f32_e32 v213, v213, v214
	ds_write_b32 v215, v213 offset:2304
.LBB0_779:
	s_or_b64 exec, exec, s[8:9]
	v_mul_f32_e32 v213, v47, v47
	s_waitcnt lgkmcnt(0)
	v_mul_f32_e32 v214, v49, v49
	v_fmac_f32_e32 v213, v46, v46
	v_fmac_f32_e32 v214, v48, v48
	v_add_f32_e32 v213, v213, v214
	v_mul_f32_e32 v214, v43, v43
	v_mul_f32_e32 v215, v45, v45
	v_fmac_f32_e32 v214, v42, v42
	v_fmac_f32_e32 v215, v44, v44
	v_add_f32_e32 v214, v214, v215
	v_add_f32_e32 v213, v213, v214
	v_mul_f32_e32 v214, v15, v15
	v_mul_f32_e32 v215, v17, v17
	v_fmac_f32_e32 v214, v14, v14
	v_fmac_f32_e32 v215, v16, v16
	v_add_f32_e32 v214, v214, v215
	v_add_f32_e32 v213, v213, v214
	v_mul_f32_e32 v214, v11, v11
	v_mul_f32_e32 v215, v13, v13
	v_fmac_f32_e32 v214, v10, v10
	v_fmac_f32_e32 v215, v12, v12
	v_add_f32_e32 v214, v214, v215
	v_add_f32_e32 v213, v213, v214
	v_mov_b32_e32 v214, v213
	s_nop 1
	v_permlane16_swap_b32_e32 v213, v214
	s_waitcnt lgkmcnt(0)
	v_add_f32_e32 v213, v213, v214
	v_mov_b32_e32 v214, v213
	s_nop 1
	v_permlane32_swap_b32_e32 v213, v214
	s_and_saveexec_b64 s[8:9], s[0:1]
	s_cbranch_execz .LBB0_781
	s_lshl_b32 s68, s2, 10
	s_add_i32 s68, s67, s68
	v_add_u32_e32 v215, s68, v223
	s_waitcnt lgkmcnt(0)
	v_add_f32_e32 v213, v213, v214
	ds_write_b32 v215, v213 offset:2560
.LBB0_781:
	s_or_b64 exec, exec, s[8:9]
	v_mul_f32_e32 v213, v35, v35
	s_waitcnt lgkmcnt(0)
	v_mul_f32_e32 v214, v37, v37
	v_fmac_f32_e32 v213, v34, v34
	v_fmac_f32_e32 v214, v36, v36
	v_add_f32_e32 v213, v213, v214
	v_mul_f32_e32 v214, v27, v27
	v_mul_f32_e32 v215, v29, v29
	v_fmac_f32_e32 v214, v26, v26
	v_fmac_f32_e32 v215, v28, v28
	v_add_f32_e32 v214, v214, v215
	v_add_f32_e32 v213, v213, v214
	v_mul_f32_e32 v214, v7, v7
	v_mul_f32_e32 v215, v9, v9
	v_fmac_f32_e32 v214, v6, v6
	v_fmac_f32_e32 v215, v8, v8
	v_add_f32_e32 v214, v214, v215
	v_add_f32_e32 v213, v213, v214
	v_mul_f32_e32 v214, v3, v3
	v_mul_f32_e32 v215, v5, v5
	v_fmac_f32_e32 v214, v2, v2
	v_fmac_f32_e32 v215, v4, v4
	v_add_f32_e32 v214, v214, v215
	v_add_f32_e32 v213, v213, v214
	v_mov_b32_e32 v194, v213
	s_nop 1
	v_permlane16_swap_b32_e32 v213, v194
	s_waitcnt lgkmcnt(0)
	v_add_f32_e32 v194, v213, v194
	v_mov_b32_e32 v212, v194
	s_nop 1
	v_permlane32_swap_b32_e32 v194, v212
	s_and_saveexec_b64 s[8:9], s[0:1]
	s_cbranch_execz .LBB0_783
	s_lshl_b32 s2, s2, 10
	s_add_i32 s67, s67, s2
	v_add_u32_e32 v213, s67, v223
	s_waitcnt lgkmcnt(0)
	v_add_f32_e32 v194, v194, v212
	ds_write_b32 v213, v194 offset:2816
